# stack19 + cache-policy hint: non-temporal (nt) stores for phase_final's f32 output (written once, never re-read)
# speedup vs baseline: 1.0093x; 1.0093x over previous
.LBB0_127:
	global_load_dwordx4 v[30:33], v[20:21], off
	global_load_dwordx4 v[34:37], v[20:21], off offset:1024
	v_add_u32_e32 v18, s12, v18
	v_cmp_lt_i32_e32 vcc, s21, v18
	s_or_b64 s[4:5], vcc, s[4:5]
	v_lshl_add_u64 v[20:21], v[20:21], 0, s[30:31]
	s_waitcnt vmcnt(0)
	v_lshlrev_b32_e32 v38, 16, v30
	v_and_b32_e32 v39, 0xffff0000, v30
	v_lshlrev_b32_e32 v30, 16, v31
	v_and_b32_e32 v31, 0xffff0000, v31
	v_pk_mul_f32 v[46:47], v[38:39], v[38:39]
	v_pk_mul_f32 v[48:49], v[30:31], v[30:31]
	v_add_f32_e32 v19, v46, v47
	v_lshlrev_b32_e32 v40, 16, v32
	v_and_b32_e32 v41, 0xffff0000, v32
	v_add_f32_e32 v19, v19, v48
	v_pk_mul_f32 v[50:51], v[40:41], v[40:41]
	v_add_f32_e32 v19, v49, v19
	v_lshlrev_b32_e32 v32, 16, v33
	v_and_b32_e32 v33, 0xffff0000, v33
	v_add_f32_e32 v19, v50, v19
	v_pk_mul_f32 v[52:53], v[32:33], v[32:33]
	v_add_f32_e32 v19, v51, v19
	s_waitcnt vmcnt(0)
	v_lshlrev_b32_e32 v42, 16, v34
	v_and_b32_e32 v43, 0xffff0000, v34
	v_add_f32_e32 v19, v52, v19
	v_pk_mul_f32 v[54:55], v[42:43], v[42:43]
	v_add_f32_e32 v19, v53, v19
	v_lshlrev_b32_e32 v34, 16, v35
	v_and_b32_e32 v35, 0xffff0000, v35
	v_add_f32_e32 v19, v54, v19
	v_pk_mul_f32 v[56:57], v[34:35], v[34:35]
	v_add_f32_e32 v19, v55, v19
	v_lshlrev_b32_e32 v44, 16, v36
	v_and_b32_e32 v45, 0xffff0000, v36
	v_add_f32_e32 v19, v56, v19
	v_pk_mul_f32 v[58:59], v[44:45], v[44:45]
	v_add_f32_e32 v19, v57, v19
	v_lshlrev_b32_e32 v36, 16, v37
	v_and_b32_e32 v37, 0xffff0000, v37
	v_add_f32_e32 v19, v58, v19
	v_pk_mul_f32 v[60:61], v[36:37], v[36:37]
	v_add_f32_e32 v19, v59, v19
	v_add_f32_e32 v19, v60, v19
	v_add_f32_e32 v19, v61, v19
	ds_bpermute_b32 v29, v0, v19
	s_waitcnt lgkmcnt(0)
	v_add_f32_e32 v19, v19, v29
	ds_bpermute_b32 v29, v24, v19
	s_waitcnt lgkmcnt(0)
	v_add_f32_e32 v19, v19, v29
	ds_bpermute_b32 v29, v25, v19
	s_waitcnt lgkmcnt(0)
	v_add_f32_e32 v19, v19, v29
	ds_bpermute_b32 v29, v26, v19
	s_waitcnt lgkmcnt(0)
	v_add_f32_e32 v19, v19, v29
	ds_bpermute_b32 v29, v27, v19
	s_waitcnt lgkmcnt(0)
	v_add_f32_e32 v19, v19, v29
	ds_bpermute_b32 v29, v28, v19
	s_waitcnt lgkmcnt(0)
	v_add_f32_e32 v19, v19, v29
	v_fmamk_f32 v19, v19, 0x3a800000, v155
	v_mul_f32_e32 v29, 0x4f800000, v19
	v_cmp_gt_f32_e32 vcc, s20, v19
	s_nop 1
	v_cndmask_b32_e32 v19, v19, v29, vcc
	v_sqrt_f32_e32 v29, v19
	s_nop 0
	v_add_u32_e32 v46, -1, v29
	v_add_u32_e32 v47, 1, v29
	v_fma_f32 v48, -v46, v29, v19
	v_fma_f32 v49, -v47, v29, v19
	v_cmp_ge_f32_e64 s[0:1], 0, v48
	s_nop 1
	v_cndmask_b32_e64 v29, v29, v46, s[0:1]
	v_cmp_lt_f32_e64 s[0:1], 0, v49
	s_nop 1
	v_cndmask_b32_e64 v29, v29, v47, s[0:1]
	v_mul_f32_e32 v46, 0x37800000, v29
	v_cndmask_b32_e32 v29, v29, v46, vcc
	v_cmp_class_f32_e32 vcc, v19, v156
	s_nop 1
	v_cndmask_b32_e32 v19, v29, v19, vcc
	v_div_scale_f32 v29, s[0:1], v19, v19, 1.0
	v_rcp_f32_e32 v47, v29
	v_div_scale_f32 v46, vcc, 1.0, v19, 1.0
	v_fma_f32 v48, -v29, v47, 1.0
	v_fmac_f32_e32 v47, v48, v47
	v_mul_f32_e32 v48, v46, v47
	v_fma_f32 v49, -v29, v48, v46
	v_fmac_f32_e32 v48, v49, v47
	v_fma_f32 v29, -v29, v48, v46
	v_div_fmas_f32 v29, v29, v47, v48
	v_div_fixup_f32 v46, v29, v19, 1.0
	v_pk_mul_f32 v[38:39], v[46:47], v[38:39] op_sel_hi:[0,1]
	v_pk_mul_f32 v[48:49], v[46:47], v[30:31] op_sel_hi:[0,1]
	v_pk_mul_f32 v[40:41], v[46:47], v[40:41] op_sel_hi:[0,1]
	v_pk_mul_f32 v[50:51], v[46:47], v[32:33] op_sel_hi:[0,1]
	v_pk_mul_f32 v[42:43], v[46:47], v[42:43] op_sel_hi:[0,1]
	v_pk_mul_f32 v[52:53], v[46:47], v[34:35] op_sel_hi:[0,1]
	v_pk_mul_f32 v[44:45], v[46:47], v[44:45] op_sel_hi:[0,1]
	v_pk_mul_f32 v[46:47], v[46:47], v[36:37] op_sel_hi:[0,1]
	v_pk_mul_f32 v[30:31], v[6:7], v[38:39]
	v_pk_mul_f32 v[32:33], v[8:9], v[48:49]
	v_pk_mul_f32 v[34:35], v[2:3], v[40:41]
	v_pk_mul_f32 v[36:37], v[4:5], v[50:51]
	v_pk_mul_f32 v[38:39], v[14:15], v[42:43]
	v_pk_mul_f32 v[40:41], v[16:17], v[52:53]
	v_pk_mul_f32 v[42:43], v[10:11], v[44:45]
	v_pk_mul_f32 v[44:45], v[12:13], v[46:47]
	global_store_dwordx4 v[22:23], v[30:33], off nt
	global_store_dwordx4 v[22:23], v[34:37], off offset:16 nt
	global_store_dwordx4 v[22:23], v[38:41], off offset:2048 nt
	global_store_dwordx4 v[22:23], v[42:45], off offset:2064 nt
	v_lshl_add_u64 v[22:23], v[22:23], 0, s[52:53]
	s_andn2_b64 exec, exec, s[4:5]
	s_cbranch_execnz .LBB0_127
